# chain ordering in 8 GEMM instances + peeled first K-iteration with srcC=0 (no accumulator zeroing) in FFN-up
# speedup vs baseline: 1.0303x; 1.0045x over previous
.LBB0_267:
	s_ashr_i32 s65, s64, 31
	s_lshl_b64 s[0:1], s[64:65], 20
	s_add_u32 s36, s94, s0
	s_addc_u32 s37, s95, s1
	s_and_b64 s[0:1], s[68:69], exec
	s_cselect_b32 s29, s37, s67
	s_cselect_b32 s65, s36, s66
	s_ashr_i32 s51, s50, 31
	s_lshl_b64 s[0:1], s[50:51], 20
	s_add_u32 s0, s97, s0
	s_addc_u32 s1, s60, s1
	s_and_b64 s[14:15], s[68:69], exec
	s_cselect_b32 s51, s1, s71
	s_cselect_b32 s30, s0, s70
	s_add_u32 s31, s66, 0x80000
	s_addc_u32 s34, s67, 0
	s_cmp_gt_i32 s64, 31
	s_cselect_b64 s[14:15], -1, 0
	s_and_b64 s[92:93], s[22:23], s[14:15]
	s_mov_b32 s35, 0
	s_waitcnt lgkmcnt(0)
	s_mov_b64 s[14:15], 0
	s_cmp_lg_u64 s[38:39], 0
	s_cbranch_scc0 .Lsp_LBB0269_plup
	s_setprio 1
.Lsp_LBB0269_plup:
	s_or_b32 s54, s35, 1
	s_lshl_b64 s[16:17], s[54:55], 7
	s_add_i32 s54, s35, 2
	s_lshl_b64 s[44:45], s[54:55], 7
	s_add_u32 s46, s66, s44
	s_addc_u32 s47, s67, s45
	s_and_b64 vcc, s[14:15], exec
	s_cselect_b32 vcc_hi, s29, s47
	s_cselect_b32 vcc_lo, s65, s46
	s_add_u32 s44, s70, s44
	s_addc_u32 s45, s71, s45
	s_and_b64 s[14:15], s[14:15], exec
	s_cselect_b32 s15, s51, s45
	s_cselect_b32 s14, s30, s44
	s_add_i32 s44, 0, 0x10000
	v_add_u32_e32 v143, s44, v140
	s_add_i32 s45, 0, 0x14000
	ds_read_b128 v[136:139], v143
	ds_read_b128 v[144:147], v143 offset:1024
	ds_read_b128 v[148:151], v143 offset:2048
	ds_read_b128 v[152:155], v143 offset:3072
	v_add_u32_e32 v143, s45, v140
	ds_read_b128 v[168:171], v143
	ds_read_b128 v[172:175], v143 offset:1024
	ds_read_b128 v[176:179], v143 offset:2048
	ds_read_b128 v[180:183], v143 offset:3072
	s_add_u32 s16, s31, s16
	s_addc_u32 s17, s34, s17
	v_lshl_add_u64 v[156:157], s[16:17], 0, v[130:131]
	s_add_i32 m0, s73, 0xc000
	ds_read_b128 v[184:187], v142
	ds_read_b128 v[188:191], v142 offset:1024
	ds_read_b128 v[192:195], v142 offset:2048
	ds_read_b128 v[196:199], v142 offset:3072
	ds_read_b128 v[200:203], v142 offset:4096
	ds_read_b128 v[204:207], v142 offset:5120
	ds_read_b128 v[216:219], v142 offset:6144
	ds_read_b128 v[220:223], v142 offset:7168
	global_load_lds_dwordx4 v[156:157], off
	v_lshl_add_u64 v[156:157], s[16:17], 0, v[132:133]
	s_add_i32 m0, s73, 0xe000
	s_nop 0
	global_load_lds_dwordx4 v[156:157], off
	s_waitcnt vmcnt(8)
	s_waitcnt lgkmcnt(0)
	s_barrier
	s_waitcnt lgkmcnt(0)
	v_mfma_f32_16x16x32_bf16 v[122:125], v[136:139], v[184:187], 0
	v_mfma_f32_16x16x32_bf16 v[122:125], v[144:147], v[188:191], v[122:125]
	v_mfma_f32_16x16x32_bf16 v[114:117], v[148:151], v[184:187], 0
	v_mfma_f32_16x16x32_bf16 v[114:117], v[152:155], v[188:191], v[114:117]
	v_mfma_f32_16x16x32_bf16 v[106:109], v[136:139], v[192:195], 0
	v_mfma_f32_16x16x32_bf16 v[106:109], v[144:147], v[196:199], v[106:109]
	v_mfma_f32_16x16x32_bf16 v[102:105], v[148:151], v[192:195], 0
	v_mfma_f32_16x16x32_bf16 v[102:105], v[152:155], v[196:199], v[102:105]
	v_mfma_f32_16x16x32_bf16 v[90:93], v[136:139], v[200:203], 0
	v_mfma_f32_16x16x32_bf16 v[90:93], v[144:147], v[204:207], v[90:93]
	v_mfma_f32_16x16x32_bf16 v[86:89], v[148:151], v[200:203], 0
	v_mfma_f32_16x16x32_bf16 v[86:89], v[152:155], v[204:207], v[86:89]
	v_mfma_f32_16x16x32_bf16 v[74:77], v[136:139], v[216:219], 0
	v_mfma_f32_16x16x32_bf16 v[74:77], v[144:147], v[220:223], v[74:77]
	v_mfma_f32_16x16x32_bf16 v[70:73], v[148:151], v[216:219], 0
	v_mfma_f32_16x16x32_bf16 v[70:73], v[152:155], v[220:223], v[70:73]
	v_mfma_f32_16x16x32_bf16 v[126:129], v[168:171], v[184:187], 0
	v_mfma_f32_16x16x32_bf16 v[126:129], v[172:175], v[188:191], v[126:129]
	v_mfma_f32_16x16x32_bf16 v[118:121], v[176:179], v[184:187], 0
	v_mfma_f32_16x16x32_bf16 v[118:121], v[180:183], v[188:191], v[118:121]
	v_mfma_f32_16x16x32_bf16 v[110:113], v[168:171], v[192:195], 0
	v_mfma_f32_16x16x32_bf16 v[110:113], v[172:175], v[196:199], v[110:113]
	v_mfma_f32_16x16x32_bf16 v[98:101], v[176:179], v[192:195], 0
	v_mfma_f32_16x16x32_bf16 v[98:101], v[180:183], v[196:199], v[98:101]
	v_mfma_f32_16x16x32_bf16 v[94:97], v[168:171], v[200:203], 0
	v_mfma_f32_16x16x32_bf16 v[94:97], v[172:175], v[204:207], v[94:97]
	v_mfma_f32_16x16x32_bf16 v[82:85], v[176:179], v[200:203], 0
	v_mfma_f32_16x16x32_bf16 v[82:85], v[180:183], v[204:207], v[82:85]
	v_mfma_f32_16x16x32_bf16 v[78:81], v[168:171], v[216:219], 0
	v_mfma_f32_16x16x32_bf16 v[78:81], v[172:175], v[220:223], v[78:81]
	v_mfma_f32_16x16x32_bf16 v[66:69], v[176:179], v[216:219], 0
	v_mfma_f32_16x16x32_bf16 v[66:69], v[180:183], v[220:223], v[66:69]
	s_barrier
	s_add_i32 s16, s44, s61
	v_lshl_add_u64 v[156:157], s[14:15], 0, v[158:159]
	s_mov_b32 m0, s16
	ds_read_b128 v[184:187], v142 offset:16384
	ds_read_b128 v[188:191], v142 offset:17408
	ds_read_b128 v[192:195], v142 offset:18432
	ds_read_b128 v[196:199], v142 offset:19456
	ds_read_b128 v[200:203], v142 offset:20480
	ds_read_b128 v[204:207], v142 offset:21504
	ds_read_b128 v[216:219], v142 offset:22528
	ds_read_b128 v[220:223], v142 offset:23552
	global_load_lds_dwordx4 v[156:157], off
	s_add_i32 m0, s16, 0x2000
	s_add_u32 s16, s14, 0x80000
	v_lshl_add_u64 v[224:225], s[14:15], 0, v[134:135]
	s_addc_u32 s17, s15, 0
	s_add_i32 s44, s45, s61
	global_load_lds_dwordx4 v[224:225], off
	v_lshl_add_u64 v[226:227], s[16:17], 0, v[158:159]
	s_mov_b32 m0, s44
	v_lshl_add_u64 v[228:229], vcc, 0, v[132:133]
	global_load_lds_dwordx4 v[226:227], off
	v_lshl_add_u64 v[226:227], s[16:17], 0, v[134:135]
	s_add_i32 m0, s44, 0x2000
	s_nop 0
	global_load_lds_dwordx4 v[226:227], off
	v_lshl_add_u64 v[226:227], vcc, 0, v[130:131]
	s_mov_b32 m0, s73
	s_nop 0
	global_load_lds_dwordx4 v[226:227], off
	s_mov_b32 m0, s75
	s_nop 0
	global_load_lds_dwordx4 v[228:229], off
	s_waitcnt vmcnt(8)
	s_waitcnt lgkmcnt(0)
	s_barrier
	s_waitcnt lgkmcnt(0)
	v_mfma_f32_16x16x32_bf16 v[58:61], v[136:139], v[184:187], 0
	v_mfma_f32_16x16x32_bf16 v[58:61], v[144:147], v[188:191], v[58:61]
	v_mfma_f32_16x16x32_bf16 v[54:57], v[148:151], v[184:187], 0
	v_mfma_f32_16x16x32_bf16 v[54:57], v[152:155], v[188:191], v[54:57]
	v_mfma_f32_16x16x32_bf16 v[42:45], v[136:139], v[192:195], 0
	v_mfma_f32_16x16x32_bf16 v[42:45], v[144:147], v[196:199], v[42:45]
	v_mfma_f32_16x16x32_bf16 v[38:41], v[148:151], v[192:195], 0
	v_mfma_f32_16x16x32_bf16 v[38:41], v[152:155], v[196:199], v[38:41]
	v_mfma_f32_16x16x32_bf16 v[26:29], v[136:139], v[200:203], 0
	v_mfma_f32_16x16x32_bf16 v[26:29], v[144:147], v[204:207], v[26:29]
	v_mfma_f32_16x16x32_bf16 v[22:25], v[148:151], v[200:203], 0
	v_mfma_f32_16x16x32_bf16 v[22:25], v[152:155], v[204:207], v[22:25]
	v_mfma_f32_16x16x32_bf16 v[10:13], v[136:139], v[216:219], 0
	v_mfma_f32_16x16x32_bf16 v[10:13], v[144:147], v[220:223], v[10:13]
	v_mfma_f32_16x16x32_bf16 v[2:5], v[148:151], v[216:219], 0
	v_mfma_f32_16x16x32_bf16 v[2:5], v[152:155], v[220:223], v[2:5]
	v_mfma_f32_16x16x32_bf16 v[62:65], v[168:171], v[184:187], 0
	v_mfma_f32_16x16x32_bf16 v[62:65], v[172:175], v[188:191], v[62:65]
	v_mfma_f32_16x16x32_bf16 v[50:53], v[176:179], v[184:187], 0
	v_mfma_f32_16x16x32_bf16 v[50:53], v[180:183], v[188:191], v[50:53]
	v_mfma_f32_16x16x32_bf16 v[46:49], v[168:171], v[192:195], 0
	v_mfma_f32_16x16x32_bf16 v[46:49], v[172:175], v[196:199], v[46:49]
	v_mfma_f32_16x16x32_bf16 v[34:37], v[176:179], v[192:195], 0
	v_mfma_f32_16x16x32_bf16 v[34:37], v[180:183], v[196:199], v[34:37]
	v_mfma_f32_16x16x32_bf16 v[30:33], v[168:171], v[200:203], 0
	v_mfma_f32_16x16x32_bf16 v[30:33], v[172:175], v[204:207], v[30:33]
	v_mfma_f32_16x16x32_bf16 v[18:21], v[176:179], v[200:203], 0
	v_mfma_f32_16x16x32_bf16 v[18:21], v[180:183], v[204:207], v[18:21]
	v_mfma_f32_16x16x32_bf16 v[14:17], v[168:171], v[216:219], 0
	v_mfma_f32_16x16x32_bf16 v[14:17], v[172:175], v[220:223], v[14:17]
	v_mfma_f32_16x16x32_bf16 v[6:9], v[176:179], v[216:219], 0
	v_mfma_f32_16x16x32_bf16 v[6:9], v[180:183], v[220:223], v[6:9]
	s_barrier
	s_add_i32 s44, 0, 0x18000
	v_add_u32_e32 v143, s44, v140
	s_add_i32 s45, 0, 0x1c000
	ds_read_b128 v[136:139], v143
	ds_read_b128 v[144:147], v143 offset:1024
	ds_read_b128 v[148:151], v143 offset:2048
	ds_read_b128 v[152:155], v143 offset:3072
	v_add_u32_e32 v143, s45, v140
	ds_read_b128 v[168:171], v143
	ds_read_b128 v[172:175], v143 offset:1024
	ds_read_b128 v[176:179], v143 offset:2048
	ds_read_b128 v[180:183], v143 offset:3072
	s_add_u32 s16, vcc_lo, 0x80000
	s_addc_u32 s17, vcc_hi, 0
	s_mov_b32 m0, s24
	v_lshl_add_u64 v[230:231], s[16:17], 0, v[130:131]
	ds_read_b128 v[184:187], v142 offset:32768
	ds_read_b128 v[188:191], v142 offset:33792
	ds_read_b128 v[192:195], v142 offset:34816
	ds_read_b128 v[196:199], v142 offset:35840
	ds_read_b128 v[200:203], v142 offset:36864
	ds_read_b128 v[204:207], v142 offset:37888
	ds_read_b128 v[216:219], v142 offset:38912
	ds_read_b128 v[220:223], v142 offset:39936
	global_load_lds_dwordx4 v[230:231], off
	v_lshl_add_u64 v[230:231], s[16:17], 0, v[132:133]
	s_mov_b32 m0, s25
	s_nop 0
	global_load_lds_dwordx4 v[230:231], off
	s_waitcnt vmcnt(8)
	s_waitcnt lgkmcnt(0)
	s_barrier
	s_waitcnt lgkmcnt(0)
	v_mfma_f32_16x16x32_bf16 v[122:125], v[136:139], v[184:187], v[122:125]
	v_mfma_f32_16x16x32_bf16 v[122:125], v[144:147], v[188:191], v[122:125]
	v_mfma_f32_16x16x32_bf16 v[114:117], v[148:151], v[184:187], v[114:117]
	v_mfma_f32_16x16x32_bf16 v[114:117], v[152:155], v[188:191], v[114:117]
	v_mfma_f32_16x16x32_bf16 v[106:109], v[136:139], v[192:195], v[106:109]
	v_mfma_f32_16x16x32_bf16 v[106:109], v[144:147], v[196:199], v[106:109]
	v_mfma_f32_16x16x32_bf16 v[102:105], v[148:151], v[192:195], v[102:105]
	v_mfma_f32_16x16x32_bf16 v[102:105], v[152:155], v[196:199], v[102:105]
	v_mfma_f32_16x16x32_bf16 v[90:93], v[136:139], v[200:203], v[90:93]
	v_mfma_f32_16x16x32_bf16 v[90:93], v[144:147], v[204:207], v[90:93]
	v_mfma_f32_16x16x32_bf16 v[86:89], v[148:151], v[200:203], v[86:89]
	v_mfma_f32_16x16x32_bf16 v[86:89], v[152:155], v[204:207], v[86:89]
	v_mfma_f32_16x16x32_bf16 v[74:77], v[136:139], v[216:219], v[74:77]
	v_mfma_f32_16x16x32_bf16 v[74:77], v[144:147], v[220:223], v[74:77]
	v_mfma_f32_16x16x32_bf16 v[70:73], v[148:151], v[216:219], v[70:73]
	v_mfma_f32_16x16x32_bf16 v[70:73], v[152:155], v[220:223], v[70:73]
	v_mfma_f32_16x16x32_bf16 v[126:129], v[168:171], v[184:187], v[126:129]
	v_mfma_f32_16x16x32_bf16 v[126:129], v[172:175], v[188:191], v[126:129]
	v_mfma_f32_16x16x32_bf16 v[118:121], v[176:179], v[184:187], v[118:121]
	v_mfma_f32_16x16x32_bf16 v[118:121], v[180:183], v[188:191], v[118:121]
	v_mfma_f32_16x16x32_bf16 v[110:113], v[168:171], v[192:195], v[110:113]
	v_mfma_f32_16x16x32_bf16 v[110:113], v[172:175], v[196:199], v[110:113]
	v_mfma_f32_16x16x32_bf16 v[98:101], v[176:179], v[192:195], v[98:101]
	v_mfma_f32_16x16x32_bf16 v[98:101], v[180:183], v[196:199], v[98:101]
	v_mfma_f32_16x16x32_bf16 v[94:97], v[168:171], v[200:203], v[94:97]
	v_mfma_f32_16x16x32_bf16 v[94:97], v[172:175], v[204:207], v[94:97]
	v_mfma_f32_16x16x32_bf16 v[82:85], v[176:179], v[200:203], v[82:85]
	v_mfma_f32_16x16x32_bf16 v[82:85], v[180:183], v[204:207], v[82:85]
	v_mfma_f32_16x16x32_bf16 v[78:81], v[168:171], v[216:219], v[78:81]
	v_mfma_f32_16x16x32_bf16 v[78:81], v[172:175], v[220:223], v[78:81]
	v_mfma_f32_16x16x32_bf16 v[66:69], v[176:179], v[216:219], v[66:69]
	v_mfma_f32_16x16x32_bf16 v[66:69], v[180:183], v[220:223], v[66:69]
	s_barrier
	s_add_i32 s16, s44, s61
	v_lshl_add_u64 v[156:157], v[156:157], 0, s[56:57]
	s_mov_b32 m0, s16
	ds_read_b128 v[184:187], v142 offset:49152
	ds_read_b128 v[188:191], v142 offset:50176
	ds_read_b128 v[192:195], v142 offset:51200
	ds_read_b128 v[196:199], v142 offset:52224
	ds_read_b128 v[200:203], v142 offset:53248
	ds_read_b128 v[204:207], v142 offset:54272
	ds_read_b128 v[216:219], v142 offset:55296
	ds_read_b128 v[220:223], v142 offset:56320
	global_load_lds_dwordx4 v[156:157], off
	s_add_i32 m0, s16, 0x2000
	s_add_u32 s14, s14, 0x80080
	v_lshl_add_u64 v[156:157], v[224:225], 0, s[56:57]
	s_addc_u32 s15, s15, 0
	s_add_i32 s16, s45, s61
	global_load_lds_dwordx4 v[156:157], off
	v_lshl_add_u64 v[156:157], s[14:15], 0, v[158:159]
	s_mov_b32 m0, s16
	s_nop 0
	global_load_lds_dwordx4 v[156:157], off
	v_lshl_add_u64 v[156:157], s[14:15], 0, v[134:135]
	s_add_i32 m0, s16, 0x2000
	s_nop 0
	global_load_lds_dwordx4 v[156:157], off
	v_lshl_add_u64 v[156:157], v[226:227], 0, s[56:57]
	s_mov_b32 m0, s26
	s_nop 0
	global_load_lds_dwordx4 v[156:157], off
	v_lshl_add_u64 v[156:157], v[228:229], 0, s[56:57]
	s_mov_b32 m0, s27
	s_nop 0
	global_load_lds_dwordx4 v[156:157], off
	s_waitcnt vmcnt(8)
	s_waitcnt lgkmcnt(0)
	s_barrier
	s_waitcnt lgkmcnt(0)
	v_mfma_f32_16x16x32_bf16 v[58:61], v[136:139], v[184:187], v[58:61]
	v_mfma_f32_16x16x32_bf16 v[58:61], v[144:147], v[188:191], v[58:61]
	v_mfma_f32_16x16x32_bf16 v[54:57], v[148:151], v[184:187], v[54:57]
	v_mfma_f32_16x16x32_bf16 v[54:57], v[152:155], v[188:191], v[54:57]
	v_mfma_f32_16x16x32_bf16 v[42:45], v[136:139], v[192:195], v[42:45]
	v_mfma_f32_16x16x32_bf16 v[42:45], v[144:147], v[196:199], v[42:45]
	v_mfma_f32_16x16x32_bf16 v[38:41], v[148:151], v[192:195], v[38:41]
	v_mfma_f32_16x16x32_bf16 v[38:41], v[152:155], v[196:199], v[38:41]
	v_mfma_f32_16x16x32_bf16 v[26:29], v[136:139], v[200:203], v[26:29]
	v_mfma_f32_16x16x32_bf16 v[26:29], v[144:147], v[204:207], v[26:29]
	v_mfma_f32_16x16x32_bf16 v[22:25], v[148:151], v[200:203], v[22:25]
	v_mfma_f32_16x16x32_bf16 v[22:25], v[152:155], v[204:207], v[22:25]
	v_mfma_f32_16x16x32_bf16 v[10:13], v[136:139], v[216:219], v[10:13]
	v_mfma_f32_16x16x32_bf16 v[10:13], v[144:147], v[220:223], v[10:13]
	v_mfma_f32_16x16x32_bf16 v[2:5], v[148:151], v[216:219], v[2:5]
	v_mfma_f32_16x16x32_bf16 v[2:5], v[152:155], v[220:223], v[2:5]
	v_mfma_f32_16x16x32_bf16 v[62:65], v[168:171], v[184:187], v[62:65]
	v_mfma_f32_16x16x32_bf16 v[62:65], v[172:175], v[188:191], v[62:65]
	v_mfma_f32_16x16x32_bf16 v[50:53], v[176:179], v[184:187], v[50:53]
	v_mfma_f32_16x16x32_bf16 v[50:53], v[180:183], v[188:191], v[50:53]
	v_mfma_f32_16x16x32_bf16 v[46:49], v[168:171], v[192:195], v[46:49]
	v_mfma_f32_16x16x32_bf16 v[46:49], v[172:175], v[196:199], v[46:49]
	v_mfma_f32_16x16x32_bf16 v[34:37], v[176:179], v[192:195], v[34:37]
	v_mfma_f32_16x16x32_bf16 v[34:37], v[180:183], v[196:199], v[34:37]
	v_mfma_f32_16x16x32_bf16 v[30:33], v[168:171], v[200:203], v[30:33]
	v_mfma_f32_16x16x32_bf16 v[30:33], v[172:175], v[204:207], v[30:33]
	v_mfma_f32_16x16x32_bf16 v[18:21], v[176:179], v[200:203], v[18:21]
	v_mfma_f32_16x16x32_bf16 v[18:21], v[180:183], v[204:207], v[18:21]
	v_mfma_f32_16x16x32_bf16 v[14:17], v[168:171], v[216:219], v[14:17]
	v_mfma_f32_16x16x32_bf16 v[14:17], v[172:175], v[220:223], v[14:17]
	v_mfma_f32_16x16x32_bf16 v[6:9], v[176:179], v[216:219], v[6:9]
	v_mfma_f32_16x16x32_bf16 v[6:9], v[180:183], v[220:223], v[6:9]
	s_barrier
	s_cmp_gt_u32 s35, 29
	s_mov_b32 s35, s54
	s_cbranch_scc1 .LBB0_279
	s_branch .LBB0_270

.LBB0_384:
	s_add_i32 s35, s14, 2
	s_add_u32 s36, s22, 0x100
	s_addc_u32 s37, s23, 0
	s_cmp_lg_u32 s34, s14
	s_cselect_b32 s14, s36, 0
	s_cselect_b32 s15, s37, 0
	s_add_u32 s40, s12, s14
	s_addc_u32 s41, s13, s15
	s_add_i32 s42, 0, 0x10000
	s_add_u32 s14, s0, s14
	v_add_u32_e32 v133, s42, v1
	s_addc_u32 s15, s1, s15
	s_add_i32 s43, 0, 0x14000
	ds_read_b128 v[144:147], v133
	ds_read_b128 v[148:151], v133 offset:1024
	ds_read_b128 v[152:155], v133 offset:2048
	ds_read_b128 v[168:171], v133 offset:3072
	v_add_u32_e32 v133, s43, v1
	ds_read_b128 v[172:175], v133
	ds_read_b128 v[176:179], v133 offset:1024
	ds_read_b128 v[180:183], v133 offset:2048
	ds_read_b128 v[184:187], v133 offset:3072
	v_lshl_add_u64 v[156:157], v[140:141], 0, s[22:23]
	s_add_i32 m0, s17, 0xc000
	ds_read_b128 v[188:191], v131
	ds_read_b128 v[192:195], v131 offset:1024
	ds_read_b128 v[196:199], v131 offset:2048
	ds_read_b128 v[200:203], v131 offset:3072
	ds_read_b128 v[204:207], v131 offset:4096
	ds_read_b128 v[216:219], v131 offset:5120
	ds_read_b128 v[220:223], v131 offset:6144
	ds_read_b128 v[224:227], v131 offset:7168
	global_load_lds_dwordx4 v[156:157], off
	v_lshl_add_u64 v[156:157], v[142:143], 0, s[22:23]
	s_add_i32 m0, s17, 0xe000
	s_nop 0
	global_load_lds_dwordx4 v[156:157], off
	s_waitcnt vmcnt(8)
	s_waitcnt lgkmcnt(0)
	s_barrier
	s_setprio 1
	s_waitcnt lgkmcnt(0)
	v_mfma_f32_16x16x32_bf16 v[126:129], v[144:147], v[188:191], v[126:129]
	v_mfma_f32_16x16x32_bf16 v[126:129], v[148:151], v[192:195], v[126:129]
	v_mfma_f32_16x16x32_bf16 v[122:125], v[152:155], v[188:191], v[122:125]
	v_mfma_f32_16x16x32_bf16 v[122:125], v[168:171], v[192:195], v[122:125]
	v_mfma_f32_16x16x32_bf16 v[110:113], v[144:147], v[196:199], v[110:113]
	v_mfma_f32_16x16x32_bf16 v[110:113], v[148:151], v[200:203], v[110:113]
	v_mfma_f32_16x16x32_bf16 v[106:109], v[152:155], v[196:199], v[106:109]
	v_mfma_f32_16x16x32_bf16 v[106:109], v[168:171], v[200:203], v[106:109]
	v_mfma_f32_16x16x32_bf16 v[94:97], v[144:147], v[204:207], v[94:97]
	v_mfma_f32_16x16x32_bf16 v[94:97], v[148:151], v[216:219], v[94:97]
	v_mfma_f32_16x16x32_bf16 v[90:93], v[152:155], v[204:207], v[90:93]
	v_mfma_f32_16x16x32_bf16 v[90:93], v[168:171], v[216:219], v[90:93]
	v_mfma_f32_16x16x32_bf16 v[78:81], v[144:147], v[220:223], v[78:81]
	v_mfma_f32_16x16x32_bf16 v[78:81], v[148:151], v[224:227], v[78:81]
	v_mfma_f32_16x16x32_bf16 v[74:77], v[152:155], v[220:223], v[74:77]
	v_mfma_f32_16x16x32_bf16 v[74:77], v[168:171], v[224:227], v[74:77]
	s_setprio 0
	s_setprio 1
	v_mfma_f32_16x16x32_bf16 v[118:121], v[172:175], v[188:191], v[118:121]
	v_mfma_f32_16x16x32_bf16 v[118:121], v[176:179], v[192:195], v[118:121]
	v_mfma_f32_16x16x32_bf16 v[114:117], v[180:183], v[188:191], v[114:117]
	v_mfma_f32_16x16x32_bf16 v[114:117], v[184:187], v[192:195], v[114:117]
	v_mfma_f32_16x16x32_bf16 v[102:105], v[172:175], v[196:199], v[102:105]
	v_mfma_f32_16x16x32_bf16 v[102:105], v[176:179], v[200:203], v[102:105]
	v_mfma_f32_16x16x32_bf16 v[98:101], v[180:183], v[196:199], v[98:101]
	v_mfma_f32_16x16x32_bf16 v[98:101], v[184:187], v[200:203], v[98:101]
	v_mfma_f32_16x16x32_bf16 v[86:89], v[172:175], v[204:207], v[86:89]
	v_mfma_f32_16x16x32_bf16 v[86:89], v[176:179], v[216:219], v[86:89]
	v_mfma_f32_16x16x32_bf16 v[82:85], v[180:183], v[204:207], v[82:85]
	v_mfma_f32_16x16x32_bf16 v[82:85], v[184:187], v[216:219], v[82:85]
	v_mfma_f32_16x16x32_bf16 v[70:73], v[172:175], v[220:223], v[70:73]
	v_mfma_f32_16x16x32_bf16 v[70:73], v[176:179], v[224:227], v[70:73]
	v_mfma_f32_16x16x32_bf16 v[66:69], v[180:183], v[220:223], v[66:69]
	v_mfma_f32_16x16x32_bf16 v[66:69], v[184:187], v[224:227], v[66:69]
	s_setprio 0
	s_barrier
	s_add_i32 s22, s42, s25
	v_lshl_add_u64 v[156:157], s[14:15], 0, v[158:159]
	s_mov_b32 m0, s22
	ds_read_b128 v[188:191], v131 offset:16384
	ds_read_b128 v[192:195], v131 offset:17408
	ds_read_b128 v[196:199], v131 offset:18432
	ds_read_b128 v[200:203], v131 offset:19456
	ds_read_b128 v[204:207], v131 offset:20480
	ds_read_b128 v[216:219], v131 offset:21504
	ds_read_b128 v[220:223], v131 offset:22528
	ds_read_b128 v[224:227], v131 offset:23552
	global_load_lds_dwordx4 v[156:157], off
	s_add_i32 m0, s22, 0x2000
	s_add_u32 s22, s14, 0x158000
	v_lshl_add_u64 v[228:229], s[14:15], 0, v[134:135]
	s_addc_u32 s23, s15, 0
	s_add_i32 s42, s43, s25
	global_load_lds_dwordx4 v[228:229], off
	v_lshl_add_u64 v[230:231], s[22:23], 0, v[158:159]
	s_mov_b32 m0, s42
	v_lshl_add_u64 v[232:233], s[40:41], 0, v[136:137]
	global_load_lds_dwordx4 v[230:231], off
	v_lshl_add_u64 v[230:231], s[22:23], 0, v[134:135]
	s_add_i32 m0, s42, 0x2000
	s_nop 0
	global_load_lds_dwordx4 v[230:231], off
	v_lshl_add_u64 v[230:231], s[40:41], 0, v[138:139]
	s_mov_b32 m0, s17
	s_nop 0
	global_load_lds_dwordx4 v[230:231], off
	s_mov_b32 m0, s26
	s_nop 0
	global_load_lds_dwordx4 v[232:233], off
	s_waitcnt vmcnt(8)
	s_waitcnt lgkmcnt(0)
	s_barrier
	s_setprio 1
	s_waitcnt lgkmcnt(0)
	v_mfma_f32_16x16x32_bf16 v[62:65], v[144:147], v[188:191], v[62:65]
	v_mfma_f32_16x16x32_bf16 v[62:65], v[148:151], v[192:195], v[62:65]
	v_mfma_f32_16x16x32_bf16 v[58:61], v[152:155], v[188:191], v[58:61]
	v_mfma_f32_16x16x32_bf16 v[58:61], v[168:171], v[192:195], v[58:61]
	v_mfma_f32_16x16x32_bf16 v[46:49], v[144:147], v[196:199], v[46:49]
	v_mfma_f32_16x16x32_bf16 v[46:49], v[148:151], v[200:203], v[46:49]
	v_mfma_f32_16x16x32_bf16 v[42:45], v[152:155], v[196:199], v[42:45]
	v_mfma_f32_16x16x32_bf16 v[42:45], v[168:171], v[200:203], v[42:45]
	v_mfma_f32_16x16x32_bf16 v[30:33], v[144:147], v[204:207], v[30:33]
	v_mfma_f32_16x16x32_bf16 v[30:33], v[148:151], v[216:219], v[30:33]
	v_mfma_f32_16x16x32_bf16 v[26:29], v[152:155], v[204:207], v[26:29]
	v_mfma_f32_16x16x32_bf16 v[26:29], v[168:171], v[216:219], v[26:29]
	v_mfma_f32_16x16x32_bf16 v[14:17], v[144:147], v[220:223], v[14:17]
	v_mfma_f32_16x16x32_bf16 v[14:17], v[148:151], v[224:227], v[14:17]
	v_mfma_f32_16x16x32_bf16 v[10:13], v[152:155], v[220:223], v[10:13]
	v_mfma_f32_16x16x32_bf16 v[10:13], v[168:171], v[224:227], v[10:13]
	s_setprio 0
	s_setprio 1
	v_mfma_f32_16x16x32_bf16 v[54:57], v[172:175], v[188:191], v[54:57]
	v_mfma_f32_16x16x32_bf16 v[54:57], v[176:179], v[192:195], v[54:57]
	v_mfma_f32_16x16x32_bf16 v[50:53], v[180:183], v[188:191], v[50:53]
	v_mfma_f32_16x16x32_bf16 v[50:53], v[184:187], v[192:195], v[50:53]
	v_mfma_f32_16x16x32_bf16 v[38:41], v[172:175], v[196:199], v[38:41]
	v_mfma_f32_16x16x32_bf16 v[38:41], v[176:179], v[200:203], v[38:41]
	v_mfma_f32_16x16x32_bf16 v[34:37], v[180:183], v[196:199], v[34:37]
	v_mfma_f32_16x16x32_bf16 v[34:37], v[184:187], v[200:203], v[34:37]
	v_mfma_f32_16x16x32_bf16 v[22:25], v[172:175], v[204:207], v[22:25]
	v_mfma_f32_16x16x32_bf16 v[22:25], v[176:179], v[216:219], v[22:25]
	v_mfma_f32_16x16x32_bf16 v[18:21], v[180:183], v[204:207], v[18:21]
	v_mfma_f32_16x16x32_bf16 v[18:21], v[184:187], v[216:219], v[18:21]
	v_mfma_f32_16x16x32_bf16 v[6:9], v[172:175], v[220:223], v[6:9]
	v_mfma_f32_16x16x32_bf16 v[6:9], v[176:179], v[224:227], v[6:9]
	v_mfma_f32_16x16x32_bf16 v[2:5], v[180:183], v[220:223], v[2:5]
	v_mfma_f32_16x16x32_bf16 v[2:5], v[184:187], v[224:227], v[2:5]
	s_setprio 0
	s_barrier
	s_add_i32 s42, 0, 0x18000
	v_add_u32_e32 v133, s42, v1
	s_add_i32 s43, 0, 0x1c000
	ds_read_b128 v[144:147], v133
	ds_read_b128 v[148:151], v133 offset:1024
	ds_read_b128 v[152:155], v133 offset:2048
	ds_read_b128 v[168:171], v133 offset:3072
	v_add_u32_e32 v133, s43, v1
	ds_read_b128 v[172:175], v133
	ds_read_b128 v[176:179], v133 offset:1024
	ds_read_b128 v[180:183], v133 offset:2048
	ds_read_b128 v[184:187], v133 offset:3072
	s_add_u32 s22, s40, 0x158000
	s_addc_u32 s23, s41, 0
	s_mov_b32 m0, s27
	v_lshl_add_u64 v[234:235], s[22:23], 0, v[138:139]
	ds_read_b128 v[188:191], v131 offset:32768
	ds_read_b128 v[192:195], v131 offset:33792
	ds_read_b128 v[196:199], v131 offset:34816
	ds_read_b128 v[200:203], v131 offset:35840
	ds_read_b128 v[204:207], v131 offset:36864
	ds_read_b128 v[216:219], v131 offset:37888
	ds_read_b128 v[220:223], v131 offset:38912
	ds_read_b128 v[224:227], v131 offset:39936
	global_load_lds_dwordx4 v[234:235], off
	v_lshl_add_u64 v[234:235], s[22:23], 0, v[136:137]
	s_mov_b32 m0, s28
	s_nop 0
	global_load_lds_dwordx4 v[234:235], off
	s_waitcnt vmcnt(8)
	s_waitcnt lgkmcnt(0)
	s_barrier
	s_setprio 1
	s_waitcnt lgkmcnt(0)
	v_mfma_f32_16x16x32_bf16 v[126:129], v[144:147], v[188:191], v[126:129]
	v_mfma_f32_16x16x32_bf16 v[126:129], v[148:151], v[192:195], v[126:129]
	v_mfma_f32_16x16x32_bf16 v[122:125], v[152:155], v[188:191], v[122:125]
	v_mfma_f32_16x16x32_bf16 v[122:125], v[168:171], v[192:195], v[122:125]
	v_mfma_f32_16x16x32_bf16 v[110:113], v[144:147], v[196:199], v[110:113]
	v_mfma_f32_16x16x32_bf16 v[110:113], v[148:151], v[200:203], v[110:113]
	v_mfma_f32_16x16x32_bf16 v[106:109], v[152:155], v[196:199], v[106:109]
	v_mfma_f32_16x16x32_bf16 v[106:109], v[168:171], v[200:203], v[106:109]
	v_mfma_f32_16x16x32_bf16 v[94:97], v[144:147], v[204:207], v[94:97]
	v_mfma_f32_16x16x32_bf16 v[94:97], v[148:151], v[216:219], v[94:97]
	v_mfma_f32_16x16x32_bf16 v[90:93], v[152:155], v[204:207], v[90:93]
	v_mfma_f32_16x16x32_bf16 v[90:93], v[168:171], v[216:219], v[90:93]
	v_mfma_f32_16x16x32_bf16 v[78:81], v[144:147], v[220:223], v[78:81]
	v_mfma_f32_16x16x32_bf16 v[78:81], v[148:151], v[224:227], v[78:81]
	v_mfma_f32_16x16x32_bf16 v[74:77], v[152:155], v[220:223], v[74:77]
	v_mfma_f32_16x16x32_bf16 v[74:77], v[168:171], v[224:227], v[74:77]
	s_setprio 0
	s_setprio 1
	v_mfma_f32_16x16x32_bf16 v[118:121], v[172:175], v[188:191], v[118:121]
	v_mfma_f32_16x16x32_bf16 v[118:121], v[176:179], v[192:195], v[118:121]
	v_mfma_f32_16x16x32_bf16 v[114:117], v[180:183], v[188:191], v[114:117]
	v_mfma_f32_16x16x32_bf16 v[114:117], v[184:187], v[192:195], v[114:117]
	v_mfma_f32_16x16x32_bf16 v[102:105], v[172:175], v[196:199], v[102:105]
	v_mfma_f32_16x16x32_bf16 v[102:105], v[176:179], v[200:203], v[102:105]
	v_mfma_f32_16x16x32_bf16 v[98:101], v[180:183], v[196:199], v[98:101]
	v_mfma_f32_16x16x32_bf16 v[98:101], v[184:187], v[200:203], v[98:101]
	v_mfma_f32_16x16x32_bf16 v[86:89], v[172:175], v[204:207], v[86:89]
	v_mfma_f32_16x16x32_bf16 v[86:89], v[176:179], v[216:219], v[86:89]
	v_mfma_f32_16x16x32_bf16 v[82:85], v[180:183], v[204:207], v[82:85]
	v_mfma_f32_16x16x32_bf16 v[82:85], v[184:187], v[216:219], v[82:85]
	v_mfma_f32_16x16x32_bf16 v[70:73], v[172:175], v[220:223], v[70:73]
	v_mfma_f32_16x16x32_bf16 v[70:73], v[176:179], v[224:227], v[70:73]
	v_mfma_f32_16x16x32_bf16 v[66:69], v[180:183], v[220:223], v[66:69]
	v_mfma_f32_16x16x32_bf16 v[66:69], v[184:187], v[224:227], v[66:69]
	s_setprio 0
	s_barrier
	s_add_i32 s22, s42, s25
	v_lshl_add_u64 v[156:157], v[156:157], 0, s[56:57]
	s_mov_b32 m0, s22
	ds_read_b128 v[188:191], v131 offset:49152
	ds_read_b128 v[192:195], v131 offset:50176
	ds_read_b128 v[196:199], v131 offset:51200
	ds_read_b128 v[200:203], v131 offset:52224
	ds_read_b128 v[204:207], v131 offset:53248
	ds_read_b128 v[216:219], v131 offset:54272
	ds_read_b128 v[220:223], v131 offset:55296
	ds_read_b128 v[224:227], v131 offset:56320
	global_load_lds_dwordx4 v[156:157], off
	s_add_i32 m0, s22, 0x2000
	s_add_u32 s14, s14, 0x158080
	v_lshl_add_u64 v[156:157], v[228:229], 0, s[56:57]
	s_addc_u32 s15, s15, 0
	s_add_i32 s22, s43, s25
	global_load_lds_dwordx4 v[156:157], off
	v_lshl_add_u64 v[156:157], s[14:15], 0, v[158:159]
	s_mov_b32 m0, s22
	s_nop 0
	global_load_lds_dwordx4 v[156:157], off
	v_lshl_add_u64 v[156:157], s[14:15], 0, v[134:135]
	s_add_i32 m0, s22, 0x2000
	s_nop 0
	global_load_lds_dwordx4 v[156:157], off
	v_lshl_add_u64 v[156:157], v[230:231], 0, s[56:57]
	s_mov_b32 m0, s29
	s_nop 0
	global_load_lds_dwordx4 v[156:157], off
	v_lshl_add_u64 v[156:157], v[232:233], 0, s[56:57]
	s_mov_b32 m0, s30
	s_nop 0
	global_load_lds_dwordx4 v[156:157], off
	s_waitcnt vmcnt(8)
	s_waitcnt lgkmcnt(0)
	s_barrier
	s_setprio 1
	s_waitcnt lgkmcnt(0)
	v_mfma_f32_16x16x32_bf16 v[62:65], v[144:147], v[188:191], v[62:65]
	v_mfma_f32_16x16x32_bf16 v[62:65], v[148:151], v[192:195], v[62:65]
	v_mfma_f32_16x16x32_bf16 v[58:61], v[152:155], v[188:191], v[58:61]
	v_mfma_f32_16x16x32_bf16 v[58:61], v[168:171], v[192:195], v[58:61]
	v_mfma_f32_16x16x32_bf16 v[46:49], v[144:147], v[196:199], v[46:49]
	v_mfma_f32_16x16x32_bf16 v[46:49], v[148:151], v[200:203], v[46:49]
	v_mfma_f32_16x16x32_bf16 v[42:45], v[152:155], v[196:199], v[42:45]
	v_mfma_f32_16x16x32_bf16 v[42:45], v[168:171], v[200:203], v[42:45]
	v_mfma_f32_16x16x32_bf16 v[30:33], v[144:147], v[204:207], v[30:33]
	v_mfma_f32_16x16x32_bf16 v[30:33], v[148:151], v[216:219], v[30:33]
	v_mfma_f32_16x16x32_bf16 v[26:29], v[152:155], v[204:207], v[26:29]
	v_mfma_f32_16x16x32_bf16 v[26:29], v[168:171], v[216:219], v[26:29]
	v_mfma_f32_16x16x32_bf16 v[14:17], v[144:147], v[220:223], v[14:17]
	v_mfma_f32_16x16x32_bf16 v[14:17], v[148:151], v[224:227], v[14:17]
	v_mfma_f32_16x16x32_bf16 v[10:13], v[152:155], v[220:223], v[10:13]
	v_mfma_f32_16x16x32_bf16 v[10:13], v[168:171], v[224:227], v[10:13]
	s_setprio 0
	s_setprio 1
	v_mfma_f32_16x16x32_bf16 v[54:57], v[172:175], v[188:191], v[54:57]
	v_mfma_f32_16x16x32_bf16 v[54:57], v[176:179], v[192:195], v[54:57]
	v_mfma_f32_16x16x32_bf16 v[50:53], v[180:183], v[188:191], v[50:53]
	v_mfma_f32_16x16x32_bf16 v[50:53], v[184:187], v[192:195], v[50:53]
	v_mfma_f32_16x16x32_bf16 v[38:41], v[172:175], v[196:199], v[38:41]
	v_mfma_f32_16x16x32_bf16 v[38:41], v[176:179], v[200:203], v[38:41]
	v_mfma_f32_16x16x32_bf16 v[34:37], v[180:183], v[196:199], v[34:37]
	v_mfma_f32_16x16x32_bf16 v[34:37], v[184:187], v[200:203], v[34:37]
	v_mfma_f32_16x16x32_bf16 v[22:25], v[172:175], v[204:207], v[22:25]
	v_mfma_f32_16x16x32_bf16 v[22:25], v[176:179], v[216:219], v[22:25]
	v_mfma_f32_16x16x32_bf16 v[18:21], v[180:183], v[204:207], v[18:21]
	v_mfma_f32_16x16x32_bf16 v[18:21], v[184:187], v[216:219], v[18:21]
	v_mfma_f32_16x16x32_bf16 v[6:9], v[172:175], v[220:223], v[6:9]
	v_mfma_f32_16x16x32_bf16 v[6:9], v[176:179], v[224:227], v[6:9]
	v_mfma_f32_16x16x32_bf16 v[2:5], v[180:183], v[220:223], v[2:5]
	v_mfma_f32_16x16x32_bf16 v[2:5], v[184:187], v[224:227], v[2:5]
	s_setprio 0
	s_barrier
	s_cmp_ge_i32 s35, s31
	s_mov_b64 s[22:23], s[36:37]
	s_mov_b32 s14, s35
	s_cbranch_scc0 .LBB0_384
	s_cmpk_lt_u32 s10, 0x100
	s_cbranch_scc0 .LBB0_387

.LBB0_1186:
	s_add_u32 s16, s38, s11
	s_addc_u32 s17, s39, 0
	s_add_u32 s21, s16, 0x100
	s_addc_u32 s24, s17, 0
	s_and_b64 s[14:15], s[64:65], exec
	s_cselect_b32 s69, s49, s24
	s_cselect_b32 s68, s48, s21
	s_add_u32 s11, s0, s11
	s_addc_u32 s14, s1, 0
	s_add_u32 s11, s11, 0x100
	s_addc_u32 s21, s14, 0
	s_add_i32 s28, 0, 0x10000
	s_and_b64 s[14:15], s[64:65], exec
	s_cselect_b32 s15, s9, s21
	s_cselect_b32 s14, s10, s11
	s_add_i32 s29, 0, 0x14000
	s_add_u32 s72, s16, 0x40080
	s_addc_u32 s73, s17, 0
	s_add_i32 s27, s28, s58
	s_add_i32 m0, s13, 0xc000
	s_add_i32 s30, s13, 0xe000
	s_add_i32 s24, s27, 0x2000
	s_add_u32 s70, s14, 0x10000
	v_add_u32_e32 v150, s28, v161
	v_add_u32_e32 v172, s29, v161
	s_addc_u32 s71, s15, 0
	s_add_i32 s26, s29, s58
	ds_read_b128 v[130:133], v150
	ds_read_b128 v[134:137], v150 offset:1024
	ds_read_b128 v[138:141], v150 offset:2048
	ds_read_b128 v[150:153], v150 offset:3072
	ds_read_b128 v[154:157], v172
	ds_read_b128 v[168:171], v172 offset:1024
	ds_read_b128 v[178:181], v172 offset:2048
	ds_read_b128 v[182:185], v172 offset:3072
	s_add_i32 s25, s26, 0x2000
	s_add_i32 s21, 0, 0x18000
	s_add_i32 s17, 0, 0x1c000
	s_add_u32 s66, s68, 0x40000
	s_addc_u32 s67, s69, 0
	s_add_i32 s16, s21, s58
	s_add_i32 s11, s16, 0x2000
	s_add_u32 s64, s14, 0x10080
	s_addc_u32 s65, s15, 0
	s_add_i32 s29, s17, s58
	s_add_i32 s28, s29, 0x2000
	v_lshl_add_u64 v[172:173], s[72:73], 0, v[142:143]
	ds_read_b128 v[186:189], v176
	ds_read_b128 v[190:193], v176 offset:1024
	ds_read_b128 v[194:197], v176 offset:2048
	ds_read_b128 v[198:201], v176 offset:3072
	ds_read_b128 v[202:205], v176 offset:4096
	ds_read_b128 v[216:219], v176 offset:5120
	ds_read_b128 v[220:223], v176 offset:6144
	ds_read_b128 v[224:227], v176 offset:7168
	global_load_lds_dwordx4 v[172:173], off
	v_lshl_add_u64 v[172:173], s[72:73], 0, v[144:145]
	s_mov_b32 m0, s30
	s_nop 0
	global_load_lds_dwordx4 v[172:173], off
	s_waitcnt vmcnt(8)
	s_waitcnt lgkmcnt(0)
	s_barrier
	s_setprio 1
	s_waitcnt lgkmcnt(0)
	v_mfma_f32_16x16x32_bf16 v[126:129], v[130:133], v[186:189], v[126:129]
	v_mfma_f32_16x16x32_bf16 v[126:129], v[134:137], v[190:193], v[126:129]
	v_mfma_f32_16x16x32_bf16 v[62:65], v[138:141], v[186:189], v[62:65]
	v_mfma_f32_16x16x32_bf16 v[62:65], v[150:153], v[190:193], v[62:65]
	v_mfma_f32_16x16x32_bf16 v[118:121], v[130:133], v[194:197], v[118:121]
	v_mfma_f32_16x16x32_bf16 v[118:121], v[134:137], v[198:201], v[118:121]
	v_mfma_f32_16x16x32_bf16 v[54:57], v[138:141], v[194:197], v[54:57]
	v_mfma_f32_16x16x32_bf16 v[54:57], v[150:153], v[198:201], v[54:57]
	v_mfma_f32_16x16x32_bf16 v[110:113], v[130:133], v[202:205], v[110:113]
	v_mfma_f32_16x16x32_bf16 v[110:113], v[134:137], v[216:219], v[110:113]
	v_mfma_f32_16x16x32_bf16 v[46:49], v[138:141], v[202:205], v[46:49]
	v_mfma_f32_16x16x32_bf16 v[46:49], v[150:153], v[216:219], v[46:49]
	v_mfma_f32_16x16x32_bf16 v[102:105], v[130:133], v[220:223], v[102:105]
	v_mfma_f32_16x16x32_bf16 v[102:105], v[134:137], v[224:227], v[102:105]
	v_mfma_f32_16x16x32_bf16 v[38:41], v[138:141], v[220:223], v[38:41]
	v_mfma_f32_16x16x32_bf16 v[38:41], v[150:153], v[224:227], v[38:41]
	s_setprio 0
	s_setprio 1
	v_mfma_f32_16x16x32_bf16 v[122:125], v[154:157], v[186:189], v[122:125]
	v_mfma_f32_16x16x32_bf16 v[122:125], v[168:171], v[190:193], v[122:125]
	v_mfma_f32_16x16x32_bf16 v[58:61], v[178:181], v[186:189], v[58:61]
	v_mfma_f32_16x16x32_bf16 v[58:61], v[182:185], v[190:193], v[58:61]
	v_mfma_f32_16x16x32_bf16 v[114:117], v[154:157], v[194:197], v[114:117]
	v_mfma_f32_16x16x32_bf16 v[114:117], v[168:171], v[198:201], v[114:117]
	v_mfma_f32_16x16x32_bf16 v[50:53], v[178:181], v[194:197], v[50:53]
	v_mfma_f32_16x16x32_bf16 v[50:53], v[182:185], v[198:201], v[50:53]
	v_mfma_f32_16x16x32_bf16 v[106:109], v[154:157], v[202:205], v[106:109]
	v_mfma_f32_16x16x32_bf16 v[106:109], v[168:171], v[216:219], v[106:109]
	v_mfma_f32_16x16x32_bf16 v[42:45], v[178:181], v[202:205], v[42:45]
	v_mfma_f32_16x16x32_bf16 v[42:45], v[182:185], v[216:219], v[42:45]
	v_mfma_f32_16x16x32_bf16 v[98:101], v[154:157], v[220:223], v[98:101]
	v_mfma_f32_16x16x32_bf16 v[98:101], v[168:171], v[224:227], v[98:101]
	v_mfma_f32_16x16x32_bf16 v[34:37], v[178:181], v[220:223], v[34:37]
	v_mfma_f32_16x16x32_bf16 v[34:37], v[182:185], v[224:227], v[34:37]
	s_setprio 0
	s_barrier
	s_mov_b32 m0, s27
	v_lshl_add_u64 v[172:173], s[14:15], 0, v[158:159]
	ds_read_b128 v[186:189], v176 offset:16384
	ds_read_b128 v[190:193], v176 offset:17408
	ds_read_b128 v[194:197], v176 offset:18432
	ds_read_b128 v[198:201], v176 offset:19456
	ds_read_b128 v[202:205], v176 offset:20480
	ds_read_b128 v[216:219], v176 offset:21504
	ds_read_b128 v[220:223], v176 offset:22528
	ds_read_b128 v[224:227], v176 offset:23552
	global_load_lds_dwordx4 v[172:173], off
	v_lshl_add_u64 v[206:207], s[14:15], 0, v[146:147]
	s_mov_b32 m0, s24
	v_lshl_add_u64 v[228:229], s[70:71], 0, v[158:159]
	global_load_lds_dwordx4 v[206:207], off
	s_mov_b32 m0, s26
	v_lshl_add_u64 v[230:231], s[68:69], 0, v[144:145]
	global_load_lds_dwordx4 v[228:229], off
	v_lshl_add_u64 v[228:229], s[70:71], 0, v[146:147]
	s_mov_b32 m0, s25
	s_nop 0
	global_load_lds_dwordx4 v[228:229], off
	v_lshl_add_u64 v[228:229], s[68:69], 0, v[142:143]
	s_mov_b32 m0, s13
	s_nop 0
	global_load_lds_dwordx4 v[228:229], off
	s_mov_b32 m0, s23
	s_nop 0
	global_load_lds_dwordx4 v[230:231], off
	s_waitcnt vmcnt(8)
	s_waitcnt lgkmcnt(0)
	s_barrier
	s_setprio 1
	s_waitcnt lgkmcnt(0)
	v_mfma_f32_16x16x32_bf16 v[94:97], v[130:133], v[186:189], v[94:97]
	v_mfma_f32_16x16x32_bf16 v[94:97], v[134:137], v[190:193], v[94:97]
	v_mfma_f32_16x16x32_bf16 v[30:33], v[138:141], v[186:189], v[30:33]
	v_mfma_f32_16x16x32_bf16 v[30:33], v[150:153], v[190:193], v[30:33]
	v_mfma_f32_16x16x32_bf16 v[86:89], v[130:133], v[194:197], v[86:89]
	v_mfma_f32_16x16x32_bf16 v[86:89], v[134:137], v[198:201], v[86:89]
	v_mfma_f32_16x16x32_bf16 v[22:25], v[138:141], v[194:197], v[22:25]
	v_mfma_f32_16x16x32_bf16 v[22:25], v[150:153], v[198:201], v[22:25]
	v_mfma_f32_16x16x32_bf16 v[78:81], v[130:133], v[202:205], v[78:81]
	v_mfma_f32_16x16x32_bf16 v[78:81], v[134:137], v[216:219], v[78:81]
	v_mfma_f32_16x16x32_bf16 v[14:17], v[138:141], v[202:205], v[14:17]
	v_mfma_f32_16x16x32_bf16 v[14:17], v[150:153], v[216:219], v[14:17]
	v_mfma_f32_16x16x32_bf16 v[70:73], v[130:133], v[220:223], v[70:73]
	v_mfma_f32_16x16x32_bf16 v[70:73], v[134:137], v[224:227], v[70:73]
	v_mfma_f32_16x16x32_bf16 v[6:9], v[138:141], v[220:223], v[6:9]
	v_mfma_f32_16x16x32_bf16 v[6:9], v[150:153], v[224:227], v[6:9]
	s_setprio 0
	s_setprio 1
	v_mfma_f32_16x16x32_bf16 v[90:93], v[154:157], v[186:189], v[90:93]
	v_mfma_f32_16x16x32_bf16 v[90:93], v[168:171], v[190:193], v[90:93]
	v_mfma_f32_16x16x32_bf16 v[26:29], v[178:181], v[186:189], v[26:29]
	v_mfma_f32_16x16x32_bf16 v[26:29], v[182:185], v[190:193], v[26:29]
	v_mfma_f32_16x16x32_bf16 v[82:85], v[154:157], v[194:197], v[82:85]
	v_mfma_f32_16x16x32_bf16 v[82:85], v[168:171], v[198:201], v[82:85]
	v_mfma_f32_16x16x32_bf16 v[18:21], v[178:181], v[194:197], v[18:21]
	v_mfma_f32_16x16x32_bf16 v[18:21], v[182:185], v[198:201], v[18:21]
	v_mfma_f32_16x16x32_bf16 v[74:77], v[154:157], v[202:205], v[74:77]
	v_mfma_f32_16x16x32_bf16 v[74:77], v[168:171], v[216:219], v[74:77]
	v_mfma_f32_16x16x32_bf16 v[10:13], v[178:181], v[202:205], v[10:13]
	v_mfma_f32_16x16x32_bf16 v[10:13], v[182:185], v[216:219], v[10:13]
	v_mfma_f32_16x16x32_bf16 v[66:69], v[154:157], v[220:223], v[66:69]
	v_mfma_f32_16x16x32_bf16 v[66:69], v[168:171], v[224:227], v[66:69]
	v_mfma_f32_16x16x32_bf16 v[2:5], v[178:181], v[220:223], v[2:5]
	v_mfma_f32_16x16x32_bf16 v[2:5], v[182:185], v[224:227], v[2:5]
	s_setprio 0
	s_barrier
	v_add_u32_e32 v150, s21, v161
	v_add_u32_e32 v177, s17, v161
	ds_read_b128 v[130:133], v150
	ds_read_b128 v[134:137], v150 offset:1024
	ds_read_b128 v[138:141], v150 offset:2048
	ds_read_b128 v[150:153], v150 offset:3072
	ds_read_b128 v[154:157], v177
	ds_read_b128 v[168:171], v177 offset:1024
	ds_read_b128 v[178:181], v177 offset:2048
	ds_read_b128 v[182:185], v177 offset:3072
	s_mov_b32 m0, s59
	v_lshl_add_u64 v[232:233], s[66:67], 0, v[142:143]
	ds_read_b128 v[186:189], v176 offset:32768
	ds_read_b128 v[190:193], v176 offset:33792
	ds_read_b128 v[194:197], v176 offset:34816
	ds_read_b128 v[198:201], v176 offset:35840
	ds_read_b128 v[202:205], v176 offset:36864
	ds_read_b128 v[216:219], v176 offset:37888
	ds_read_b128 v[220:223], v176 offset:38912
	ds_read_b128 v[224:227], v176 offset:39936
	global_load_lds_dwordx4 v[232:233], off
	v_lshl_add_u64 v[232:233], s[66:67], 0, v[144:145]
	s_mov_b32 m0, s31
	s_nop 0
	global_load_lds_dwordx4 v[232:233], off
	s_waitcnt vmcnt(8)
	s_waitcnt lgkmcnt(0)
	s_barrier
	s_setprio 1
	s_waitcnt lgkmcnt(0)
	v_mfma_f32_16x16x32_bf16 v[126:129], v[130:133], v[186:189], v[126:129]
	v_mfma_f32_16x16x32_bf16 v[126:129], v[134:137], v[190:193], v[126:129]
	v_mfma_f32_16x16x32_bf16 v[62:65], v[138:141], v[186:189], v[62:65]
	v_mfma_f32_16x16x32_bf16 v[62:65], v[150:153], v[190:193], v[62:65]
	v_mfma_f32_16x16x32_bf16 v[118:121], v[130:133], v[194:197], v[118:121]
	v_mfma_f32_16x16x32_bf16 v[118:121], v[134:137], v[198:201], v[118:121]
	v_mfma_f32_16x16x32_bf16 v[54:57], v[138:141], v[194:197], v[54:57]
	v_mfma_f32_16x16x32_bf16 v[54:57], v[150:153], v[198:201], v[54:57]
	v_mfma_f32_16x16x32_bf16 v[110:113], v[130:133], v[202:205], v[110:113]
	v_mfma_f32_16x16x32_bf16 v[110:113], v[134:137], v[216:219], v[110:113]
	v_mfma_f32_16x16x32_bf16 v[46:49], v[138:141], v[202:205], v[46:49]
	v_mfma_f32_16x16x32_bf16 v[46:49], v[150:153], v[216:219], v[46:49]
	v_mfma_f32_16x16x32_bf16 v[102:105], v[130:133], v[220:223], v[102:105]
	v_mfma_f32_16x16x32_bf16 v[102:105], v[134:137], v[224:227], v[102:105]
	v_mfma_f32_16x16x32_bf16 v[38:41], v[138:141], v[220:223], v[38:41]
	v_mfma_f32_16x16x32_bf16 v[38:41], v[150:153], v[224:227], v[38:41]
	s_setprio 0
	s_setprio 1
	v_mfma_f32_16x16x32_bf16 v[122:125], v[154:157], v[186:189], v[122:125]
	v_mfma_f32_16x16x32_bf16 v[122:125], v[168:171], v[190:193], v[122:125]
	v_mfma_f32_16x16x32_bf16 v[58:61], v[178:181], v[186:189], v[58:61]
	v_mfma_f32_16x16x32_bf16 v[58:61], v[182:185], v[190:193], v[58:61]
	v_mfma_f32_16x16x32_bf16 v[114:117], v[154:157], v[194:197], v[114:117]
	v_mfma_f32_16x16x32_bf16 v[114:117], v[168:171], v[198:201], v[114:117]
	v_mfma_f32_16x16x32_bf16 v[50:53], v[178:181], v[194:197], v[50:53]
	v_mfma_f32_16x16x32_bf16 v[50:53], v[182:185], v[198:201], v[50:53]
	v_mfma_f32_16x16x32_bf16 v[106:109], v[154:157], v[202:205], v[106:109]
	v_mfma_f32_16x16x32_bf16 v[106:109], v[168:171], v[216:219], v[106:109]
	v_mfma_f32_16x16x32_bf16 v[42:45], v[178:181], v[202:205], v[42:45]
	v_mfma_f32_16x16x32_bf16 v[42:45], v[182:185], v[216:219], v[42:45]
	v_mfma_f32_16x16x32_bf16 v[98:101], v[154:157], v[220:223], v[98:101]
	v_mfma_f32_16x16x32_bf16 v[98:101], v[168:171], v[224:227], v[98:101]
	v_mfma_f32_16x16x32_bf16 v[34:37], v[178:181], v[220:223], v[34:37]
	v_mfma_f32_16x16x32_bf16 v[34:37], v[182:185], v[224:227], v[34:37]
	s_setprio 0
	s_barrier
	s_mov_b32 m0, s16
	v_lshl_add_u64 v[172:173], v[172:173], 0, s[56:57]
	ds_read_b128 v[186:189], v176 offset:49152
	ds_read_b128 v[190:193], v176 offset:50176
	ds_read_b128 v[194:197], v176 offset:51200
	ds_read_b128 v[198:201], v176 offset:52224
	ds_read_b128 v[202:205], v176 offset:53248
	ds_read_b128 v[216:219], v176 offset:54272
	ds_read_b128 v[220:223], v176 offset:55296
	ds_read_b128 v[224:227], v176 offset:56320
	global_load_lds_dwordx4 v[172:173], off
	v_lshl_add_u64 v[172:173], v[206:207], 0, s[56:57]
	s_mov_b32 m0, s11
	s_nop 0
	global_load_lds_dwordx4 v[172:173], off
	v_lshl_add_u64 v[172:173], s[64:65], 0, v[158:159]
	s_mov_b32 m0, s29
	s_nop 0
	global_load_lds_dwordx4 v[172:173], off
	v_lshl_add_u64 v[172:173], s[64:65], 0, v[146:147]
	s_mov_b32 m0, s28
	s_nop 0
	global_load_lds_dwordx4 v[172:173], off
	v_lshl_add_u64 v[172:173], v[228:229], 0, s[56:57]
	s_mov_b32 m0, s75
	s_nop 0
	global_load_lds_dwordx4 v[172:173], off
	v_lshl_add_u64 v[172:173], v[230:231], 0, s[56:57]
	s_mov_b32 m0, s92
	s_nop 0
	global_load_lds_dwordx4 v[172:173], off
	s_waitcnt vmcnt(8)
	s_waitcnt lgkmcnt(0)
	s_barrier
	s_setprio 1
	s_waitcnt lgkmcnt(0)
	v_mfma_f32_16x16x32_bf16 v[94:97], v[130:133], v[186:189], v[94:97]
	v_mfma_f32_16x16x32_bf16 v[94:97], v[134:137], v[190:193], v[94:97]
	v_mfma_f32_16x16x32_bf16 v[30:33], v[138:141], v[186:189], v[30:33]
	v_mfma_f32_16x16x32_bf16 v[30:33], v[150:153], v[190:193], v[30:33]
	v_mfma_f32_16x16x32_bf16 v[86:89], v[130:133], v[194:197], v[86:89]
	v_mfma_f32_16x16x32_bf16 v[86:89], v[134:137], v[198:201], v[86:89]
	v_mfma_f32_16x16x32_bf16 v[22:25], v[138:141], v[194:197], v[22:25]
	v_mfma_f32_16x16x32_bf16 v[22:25], v[150:153], v[198:201], v[22:25]
	v_mfma_f32_16x16x32_bf16 v[78:81], v[130:133], v[202:205], v[78:81]
	v_mfma_f32_16x16x32_bf16 v[78:81], v[134:137], v[216:219], v[78:81]
	v_mfma_f32_16x16x32_bf16 v[14:17], v[138:141], v[202:205], v[14:17]
	v_mfma_f32_16x16x32_bf16 v[14:17], v[150:153], v[216:219], v[14:17]
	v_mfma_f32_16x16x32_bf16 v[70:73], v[130:133], v[220:223], v[70:73]
	v_mfma_f32_16x16x32_bf16 v[70:73], v[134:137], v[224:227], v[70:73]
	v_mfma_f32_16x16x32_bf16 v[6:9], v[138:141], v[220:223], v[6:9]
	v_mfma_f32_16x16x32_bf16 v[6:9], v[150:153], v[224:227], v[6:9]
	s_setprio 0
	s_setprio 1
	v_mfma_f32_16x16x32_bf16 v[90:93], v[154:157], v[186:189], v[90:93]
	v_mfma_f32_16x16x32_bf16 v[90:93], v[168:171], v[190:193], v[90:93]
	v_mfma_f32_16x16x32_bf16 v[26:29], v[178:181], v[186:189], v[26:29]
	v_mfma_f32_16x16x32_bf16 v[26:29], v[182:185], v[190:193], v[26:29]
	v_mfma_f32_16x16x32_bf16 v[82:85], v[154:157], v[194:197], v[82:85]
	v_mfma_f32_16x16x32_bf16 v[82:85], v[168:171], v[198:201], v[82:85]
	v_mfma_f32_16x16x32_bf16 v[18:21], v[178:181], v[194:197], v[18:21]
	v_mfma_f32_16x16x32_bf16 v[18:21], v[182:185], v[198:201], v[18:21]
	v_mfma_f32_16x16x32_bf16 v[74:77], v[154:157], v[202:205], v[74:77]
	v_mfma_f32_16x16x32_bf16 v[74:77], v[168:171], v[216:219], v[74:77]
	v_mfma_f32_16x16x32_bf16 v[10:13], v[178:181], v[202:205], v[10:13]
	v_mfma_f32_16x16x32_bf16 v[10:13], v[182:185], v[216:219], v[10:13]
	v_mfma_f32_16x16x32_bf16 v[66:69], v[154:157], v[220:223], v[66:69]
	v_mfma_f32_16x16x32_bf16 v[66:69], v[168:171], v[224:227], v[66:69]
	v_mfma_f32_16x16x32_bf16 v[2:5], v[178:181], v[220:223], v[2:5]
	v_mfma_f32_16x16x32_bf16 v[2:5], v[182:185], v[224:227], v[2:5]
	s_setprio 0
	s_barrier
	s_movk_i32 s11, 0x100
	s_andn2_b64 vcc, exec, s[40:41]
	s_mov_b64 s[64:65], -1
	s_mov_b64 s[40:41], 0
	s_cbranch_vccz .LBB0_1186
	v_readlane_b32 s0, v241, 17
	v_readlane_b32 s1, v241, 18
	s_and_b64 vcc, exec, s[0:1]
	s_cbranch_vccz .LBB0_1189
	s_barrier

.LBB0_1460:
	s_add_u32 s23, s50, s14
	s_addc_u32 s28, s51, 0
	s_add_u32 s15, s23, 0x100
	s_addc_u32 s29, s28, 0
	s_and_b64 s[26:27], s[66:67], exec
	s_cselect_b32 s71, s43, s29
	s_cselect_b32 s70, s42, s15
	s_add_u32 s14, s0, s14
	s_addc_u32 s15, s1, 0
	s_add_u32 s26, s14, 0x100
	s_addc_u32 s27, s15, 0
	s_add_i32 s35, 0, 0x10000
	s_and_b64 s[14:15], s[66:67], exec
	s_cselect_b32 s15, s16, s27
	s_cselect_b32 s14, s17, s26
	s_add_i32 s39, 0, 0x14000
	s_add_u32 s74, s23, 0x40080
	s_addc_u32 s75, s28, 0
	s_add_i32 s34, s35, s11
	s_add_i32 m0, s53, 0xc000
	s_add_i32 s41, s53, 0xe000
	s_add_i32 s29, s34, 0x2000
	v_add_u32_e32 v151, s35, v148
	s_add_u32 s72, s14, 0x10000
	ds_read_b128 v[102:105], v151
	ds_read_b128 v[110:113], v151 offset:1024
	ds_read_b128 v[144:147], v151 offset:2048
	ds_read_b128 v[152:155], v151 offset:3072
	v_add_u32_e32 v151, s39, v148
	s_addc_u32 s73, s15, 0
	s_add_i32 s31, s39, s11
	ds_read_b128 v[168:171], v151
	ds_read_b128 v[172:175], v151 offset:1024
	ds_read_b128 v[176:179], v151 offset:2048
	ds_read_b128 v[180:183], v151 offset:3072
	s_add_i32 s30, s31, 0x2000
	s_add_i32 s28, 0, 0x18000
	s_add_i32 s27, 0, 0x1c000
	s_add_u32 s68, s70, 0x40000
	s_addc_u32 s69, s71, 0
	s_add_i32 s26, s28, s11
	s_add_i32 s23, s26, 0x2000
	s_add_u32 s66, s14, 0x10080
	s_addc_u32 s67, s15, 0
	s_add_i32 s39, s27, s11
	s_add_i32 s35, s39, 0x2000
	v_lshl_add_u64 v[156:157], s[74:75], 0, v[142:143]
	ds_read_b128 v[184:187], v150
	ds_read_b128 v[188:191], v150 offset:1024
	ds_read_b128 v[192:195], v150 offset:2048
	ds_read_b128 v[196:199], v150 offset:3072
	ds_read_b128 v[200:203], v150 offset:4096
	ds_read_b128 v[204:207], v150 offset:5120
	ds_read_b128 v[216:219], v150 offset:6144
	ds_read_b128 v[220:223], v150 offset:7168
	global_load_lds_dwordx4 v[156:157], off
	v_lshl_add_u64 v[156:157], s[74:75], 0, v[140:141]
	s_mov_b32 m0, s41
	s_nop 0
	global_load_lds_dwordx4 v[156:157], off
	s_waitcnt vmcnt(8)
	s_waitcnt lgkmcnt(0)
	s_barrier
	s_setprio 1
	s_waitcnt lgkmcnt(0)
	v_mfma_f32_16x16x32_bf16 v[134:137], v[102:105], v[184:187], v[134:137]
	v_mfma_f32_16x16x32_bf16 v[134:137], v[110:113], v[188:191], v[134:137]
	v_mfma_f32_16x16x32_bf16 v[130:133], v[144:147], v[184:187], v[130:133]
	v_mfma_f32_16x16x32_bf16 v[130:133], v[152:155], v[188:191], v[130:133]
	v_mfma_f32_16x16x32_bf16 v[126:129], v[102:105], v[192:195], v[126:129]
	v_mfma_f32_16x16x32_bf16 v[126:129], v[110:113], v[196:199], v[126:129]
	v_mfma_f32_16x16x32_bf16 v[122:125], v[144:147], v[192:195], v[122:125]
	v_mfma_f32_16x16x32_bf16 v[122:125], v[152:155], v[196:199], v[122:125]
	v_mfma_f32_16x16x32_bf16 v[118:121], v[102:105], v[200:203], v[118:121]
	v_mfma_f32_16x16x32_bf16 v[118:121], v[110:113], v[204:207], v[118:121]
	v_mfma_f32_16x16x32_bf16 v[114:117], v[144:147], v[200:203], v[114:117]
	v_mfma_f32_16x16x32_bf16 v[114:117], v[152:155], v[204:207], v[114:117]
	v_mfma_f32_16x16x32_bf16 v[106:109], v[102:105], v[216:219], v[106:109]
	v_mfma_f32_16x16x32_bf16 v[106:109], v[110:113], v[220:223], v[106:109]
	v_mfma_f32_16x16x32_bf16 v[98:101], v[144:147], v[216:219], v[98:101]
	v_mfma_f32_16x16x32_bf16 v[98:101], v[152:155], v[220:223], v[98:101]
	s_setprio 0
	s_setprio 1
	v_mfma_f32_16x16x32_bf16 v[66:69], v[168:171], v[184:187], v[66:69]
	v_mfma_f32_16x16x32_bf16 v[66:69], v[172:175], v[188:191], v[66:69]
	v_mfma_f32_16x16x32_bf16 v[58:61], v[176:179], v[184:187], v[58:61]
	v_mfma_f32_16x16x32_bf16 v[58:61], v[180:183], v[188:191], v[58:61]
	v_mfma_f32_16x16x32_bf16 v[54:57], v[168:171], v[192:195], v[54:57]
	v_mfma_f32_16x16x32_bf16 v[54:57], v[172:175], v[196:199], v[54:57]
	v_mfma_f32_16x16x32_bf16 v[50:53], v[176:179], v[192:195], v[50:53]
	v_mfma_f32_16x16x32_bf16 v[50:53], v[180:183], v[196:199], v[50:53]
	v_mfma_f32_16x16x32_bf16 v[46:49], v[168:171], v[200:203], v[46:49]
	v_mfma_f32_16x16x32_bf16 v[46:49], v[172:175], v[204:207], v[46:49]
	v_mfma_f32_16x16x32_bf16 v[42:45], v[176:179], v[200:203], v[42:45]
	v_mfma_f32_16x16x32_bf16 v[42:45], v[180:183], v[204:207], v[42:45]
	v_mfma_f32_16x16x32_bf16 v[38:41], v[168:171], v[216:219], v[38:41]
	v_mfma_f32_16x16x32_bf16 v[38:41], v[172:175], v[220:223], v[38:41]
	v_mfma_f32_16x16x32_bf16 v[34:37], v[176:179], v[216:219], v[34:37]
	v_mfma_f32_16x16x32_bf16 v[34:37], v[180:183], v[220:223], v[34:37]
	s_setprio 0
	s_barrier
	s_mov_b32 m0, s34
	v_lshl_add_u64 v[156:157], s[14:15], 0, v[158:159]
	ds_read_b128 v[184:187], v150 offset:16384
	ds_read_b128 v[188:191], v150 offset:17408
	ds_read_b128 v[192:195], v150 offset:18432
	ds_read_b128 v[196:199], v150 offset:19456
	ds_read_b128 v[200:203], v150 offset:20480
	ds_read_b128 v[204:207], v150 offset:21504
	ds_read_b128 v[216:219], v150 offset:22528
	ds_read_b128 v[220:223], v150 offset:23552
	global_load_lds_dwordx4 v[156:157], off
	v_lshl_add_u64 v[224:225], s[14:15], 0, v[138:139]
	s_mov_b32 m0, s29
	v_lshl_add_u64 v[226:227], s[72:73], 0, v[158:159]
	global_load_lds_dwordx4 v[224:225], off
	s_mov_b32 m0, s31
	v_lshl_add_u64 v[228:229], s[70:71], 0, v[140:141]
	global_load_lds_dwordx4 v[226:227], off
	v_lshl_add_u64 v[226:227], s[72:73], 0, v[138:139]
	s_mov_b32 m0, s30
	s_nop 0
	global_load_lds_dwordx4 v[226:227], off
	v_lshl_add_u64 v[226:227], s[70:71], 0, v[142:143]
	s_mov_b32 m0, s53
	s_nop 0
	global_load_lds_dwordx4 v[226:227], off
	s_mov_b32 m0, s58
	s_nop 0
	global_load_lds_dwordx4 v[228:229], off
	s_waitcnt vmcnt(8)
	s_waitcnt lgkmcnt(0)
	s_barrier
	s_setprio 1
	s_waitcnt lgkmcnt(0)
	v_mfma_f32_16x16x32_bf16 v[94:97], v[102:105], v[184:187], v[94:97]
	v_mfma_f32_16x16x32_bf16 v[94:97], v[110:113], v[188:191], v[94:97]
	v_mfma_f32_16x16x32_bf16 v[90:93], v[144:147], v[184:187], v[90:93]
	v_mfma_f32_16x16x32_bf16 v[90:93], v[152:155], v[188:191], v[90:93]
	v_mfma_f32_16x16x32_bf16 v[86:89], v[102:105], v[192:195], v[86:89]
	v_mfma_f32_16x16x32_bf16 v[86:89], v[110:113], v[196:199], v[86:89]
	v_mfma_f32_16x16x32_bf16 v[82:85], v[144:147], v[192:195], v[82:85]
	v_mfma_f32_16x16x32_bf16 v[82:85], v[152:155], v[196:199], v[82:85]
	v_mfma_f32_16x16x32_bf16 v[78:81], v[102:105], v[200:203], v[78:81]
	v_mfma_f32_16x16x32_bf16 v[78:81], v[110:113], v[204:207], v[78:81]
	v_mfma_f32_16x16x32_bf16 v[74:77], v[144:147], v[200:203], v[74:77]
	v_mfma_f32_16x16x32_bf16 v[74:77], v[152:155], v[204:207], v[74:77]
	v_mfma_f32_16x16x32_bf16 v[70:73], v[102:105], v[216:219], v[70:73]
	v_mfma_f32_16x16x32_bf16 v[70:73], v[110:113], v[220:223], v[70:73]
	v_mfma_f32_16x16x32_bf16 v[62:65], v[144:147], v[216:219], v[62:65]
	v_mfma_f32_16x16x32_bf16 v[62:65], v[152:155], v[220:223], v[62:65]
	s_setprio 0
	s_setprio 1
	v_mfma_f32_16x16x32_bf16 v[30:33], v[168:171], v[184:187], v[30:33]
	v_mfma_f32_16x16x32_bf16 v[30:33], v[172:175], v[188:191], v[30:33]
	v_mfma_f32_16x16x32_bf16 v[26:29], v[176:179], v[184:187], v[26:29]
	v_mfma_f32_16x16x32_bf16 v[26:29], v[180:183], v[188:191], v[26:29]
	v_mfma_f32_16x16x32_bf16 v[22:25], v[168:171], v[192:195], v[22:25]
	v_mfma_f32_16x16x32_bf16 v[22:25], v[172:175], v[196:199], v[22:25]
	v_mfma_f32_16x16x32_bf16 v[18:21], v[176:179], v[192:195], v[18:21]
	v_mfma_f32_16x16x32_bf16 v[18:21], v[180:183], v[196:199], v[18:21]
	v_mfma_f32_16x16x32_bf16 v[14:17], v[168:171], v[200:203], v[14:17]
	v_mfma_f32_16x16x32_bf16 v[14:17], v[172:175], v[204:207], v[14:17]
	v_mfma_f32_16x16x32_bf16 v[10:13], v[176:179], v[200:203], v[10:13]
	v_mfma_f32_16x16x32_bf16 v[10:13], v[180:183], v[204:207], v[10:13]
	v_mfma_f32_16x16x32_bf16 v[6:9], v[168:171], v[216:219], v[6:9]
	v_mfma_f32_16x16x32_bf16 v[6:9], v[172:175], v[220:223], v[6:9]
	v_mfma_f32_16x16x32_bf16 v[2:5], v[176:179], v[216:219], v[2:5]
	v_mfma_f32_16x16x32_bf16 v[2:5], v[180:183], v[220:223], v[2:5]
	s_setprio 0
	s_barrier
	v_add_u32_e32 v151, s28, v148
	ds_read_b128 v[102:105], v151
	ds_read_b128 v[110:113], v151 offset:1024
	ds_read_b128 v[144:147], v151 offset:2048
	ds_read_b128 v[152:155], v151 offset:3072
	v_add_u32_e32 v151, s27, v148
	ds_read_b128 v[168:171], v151
	ds_read_b128 v[172:175], v151 offset:1024
	ds_read_b128 v[176:179], v151 offset:2048
	ds_read_b128 v[180:183], v151 offset:3072
	s_mov_b32 m0, s59
	v_lshl_add_u64 v[230:231], s[68:69], 0, v[142:143]
	ds_read_b128 v[184:187], v150 offset:32768
	ds_read_b128 v[188:191], v150 offset:33792
	ds_read_b128 v[192:195], v150 offset:34816
	ds_read_b128 v[196:199], v150 offset:35840
	ds_read_b128 v[200:203], v150 offset:36864
	ds_read_b128 v[204:207], v150 offset:37888
	ds_read_b128 v[216:219], v150 offset:38912
	ds_read_b128 v[220:223], v150 offset:39936
	global_load_lds_dwordx4 v[230:231], off
	v_lshl_add_u64 v[230:231], s[68:69], 0, v[140:141]
	s_mov_b32 m0, s92
	s_nop 0
	global_load_lds_dwordx4 v[230:231], off
	s_waitcnt vmcnt(8)
	s_waitcnt lgkmcnt(0)
	s_barrier
	s_setprio 1
	s_waitcnt lgkmcnt(0)
	v_mfma_f32_16x16x32_bf16 v[134:137], v[102:105], v[184:187], v[134:137]
	v_mfma_f32_16x16x32_bf16 v[134:137], v[110:113], v[188:191], v[134:137]
	v_mfma_f32_16x16x32_bf16 v[130:133], v[144:147], v[184:187], v[130:133]
	v_mfma_f32_16x16x32_bf16 v[130:133], v[152:155], v[188:191], v[130:133]
	v_mfma_f32_16x16x32_bf16 v[126:129], v[102:105], v[192:195], v[126:129]
	v_mfma_f32_16x16x32_bf16 v[126:129], v[110:113], v[196:199], v[126:129]
	v_mfma_f32_16x16x32_bf16 v[122:125], v[144:147], v[192:195], v[122:125]
	v_mfma_f32_16x16x32_bf16 v[122:125], v[152:155], v[196:199], v[122:125]
	v_mfma_f32_16x16x32_bf16 v[118:121], v[102:105], v[200:203], v[118:121]
	v_mfma_f32_16x16x32_bf16 v[118:121], v[110:113], v[204:207], v[118:121]
	v_mfma_f32_16x16x32_bf16 v[114:117], v[144:147], v[200:203], v[114:117]
	v_mfma_f32_16x16x32_bf16 v[114:117], v[152:155], v[204:207], v[114:117]
	v_mfma_f32_16x16x32_bf16 v[106:109], v[102:105], v[216:219], v[106:109]
	v_mfma_f32_16x16x32_bf16 v[106:109], v[110:113], v[220:223], v[106:109]
	v_mfma_f32_16x16x32_bf16 v[98:101], v[144:147], v[216:219], v[98:101]
	v_mfma_f32_16x16x32_bf16 v[98:101], v[152:155], v[220:223], v[98:101]
	s_setprio 0
	s_setprio 1
	v_mfma_f32_16x16x32_bf16 v[66:69], v[168:171], v[184:187], v[66:69]
	v_mfma_f32_16x16x32_bf16 v[66:69], v[172:175], v[188:191], v[66:69]
	v_mfma_f32_16x16x32_bf16 v[58:61], v[176:179], v[184:187], v[58:61]
	v_mfma_f32_16x16x32_bf16 v[58:61], v[180:183], v[188:191], v[58:61]
	v_mfma_f32_16x16x32_bf16 v[54:57], v[168:171], v[192:195], v[54:57]
	v_mfma_f32_16x16x32_bf16 v[54:57], v[172:175], v[196:199], v[54:57]
	v_mfma_f32_16x16x32_bf16 v[50:53], v[176:179], v[192:195], v[50:53]
	v_mfma_f32_16x16x32_bf16 v[50:53], v[180:183], v[196:199], v[50:53]
	v_mfma_f32_16x16x32_bf16 v[46:49], v[168:171], v[200:203], v[46:49]
	v_mfma_f32_16x16x32_bf16 v[46:49], v[172:175], v[204:207], v[46:49]
	v_mfma_f32_16x16x32_bf16 v[42:45], v[176:179], v[200:203], v[42:45]
	v_mfma_f32_16x16x32_bf16 v[42:45], v[180:183], v[204:207], v[42:45]
	v_mfma_f32_16x16x32_bf16 v[38:41], v[168:171], v[216:219], v[38:41]
	v_mfma_f32_16x16x32_bf16 v[38:41], v[172:175], v[220:223], v[38:41]
	v_mfma_f32_16x16x32_bf16 v[34:37], v[176:179], v[216:219], v[34:37]
	v_mfma_f32_16x16x32_bf16 v[34:37], v[180:183], v[220:223], v[34:37]
	s_setprio 0
	s_barrier
	s_mov_b32 m0, s26
	v_lshl_add_u64 v[156:157], v[156:157], 0, s[56:57]
	ds_read_b128 v[184:187], v150 offset:49152
	ds_read_b128 v[188:191], v150 offset:50176
	ds_read_b128 v[192:195], v150 offset:51200
	ds_read_b128 v[196:199], v150 offset:52224
	ds_read_b128 v[200:203], v150 offset:53248
	ds_read_b128 v[204:207], v150 offset:54272
	ds_read_b128 v[216:219], v150 offset:55296
	ds_read_b128 v[220:223], v150 offset:56320
	global_load_lds_dwordx4 v[156:157], off
	v_lshl_add_u64 v[156:157], v[224:225], 0, s[56:57]
	s_mov_b32 m0, s23
	s_nop 0
	global_load_lds_dwordx4 v[156:157], off
	v_lshl_add_u64 v[156:157], s[66:67], 0, v[158:159]
	s_mov_b32 m0, s39
	s_nop 0
	global_load_lds_dwordx4 v[156:157], off
	v_lshl_add_u64 v[156:157], s[66:67], 0, v[138:139]
	s_mov_b32 m0, s35
	s_nop 0
	global_load_lds_dwordx4 v[156:157], off
	v_lshl_add_u64 v[156:157], v[226:227], 0, s[56:57]
	s_mov_b32 m0, s54
	s_nop 0
	global_load_lds_dwordx4 v[156:157], off
	v_lshl_add_u64 v[156:157], v[228:229], 0, s[56:57]
	s_mov_b32 m0, s60
	s_nop 0
	global_load_lds_dwordx4 v[156:157], off
	s_waitcnt vmcnt(8)
	s_waitcnt lgkmcnt(0)
	s_barrier
	s_setprio 1
	s_waitcnt lgkmcnt(0)
	v_mfma_f32_16x16x32_bf16 v[94:97], v[102:105], v[184:187], v[94:97]
	v_mfma_f32_16x16x32_bf16 v[94:97], v[110:113], v[188:191], v[94:97]
	v_mfma_f32_16x16x32_bf16 v[90:93], v[144:147], v[184:187], v[90:93]
	v_mfma_f32_16x16x32_bf16 v[90:93], v[152:155], v[188:191], v[90:93]
	v_mfma_f32_16x16x32_bf16 v[86:89], v[102:105], v[192:195], v[86:89]
	v_mfma_f32_16x16x32_bf16 v[86:89], v[110:113], v[196:199], v[86:89]
	v_mfma_f32_16x16x32_bf16 v[82:85], v[144:147], v[192:195], v[82:85]
	v_mfma_f32_16x16x32_bf16 v[82:85], v[152:155], v[196:199], v[82:85]
	v_mfma_f32_16x16x32_bf16 v[78:81], v[102:105], v[200:203], v[78:81]
	v_mfma_f32_16x16x32_bf16 v[78:81], v[110:113], v[204:207], v[78:81]
	v_mfma_f32_16x16x32_bf16 v[74:77], v[144:147], v[200:203], v[74:77]
	v_mfma_f32_16x16x32_bf16 v[74:77], v[152:155], v[204:207], v[74:77]
	v_mfma_f32_16x16x32_bf16 v[70:73], v[102:105], v[216:219], v[70:73]
	v_mfma_f32_16x16x32_bf16 v[70:73], v[110:113], v[220:223], v[70:73]
	v_mfma_f32_16x16x32_bf16 v[62:65], v[144:147], v[216:219], v[62:65]
	v_mfma_f32_16x16x32_bf16 v[62:65], v[152:155], v[220:223], v[62:65]
	s_setprio 0
	s_setprio 1
	v_mfma_f32_16x16x32_bf16 v[30:33], v[168:171], v[184:187], v[30:33]
	v_mfma_f32_16x16x32_bf16 v[30:33], v[172:175], v[188:191], v[30:33]
	v_mfma_f32_16x16x32_bf16 v[26:29], v[176:179], v[184:187], v[26:29]
	v_mfma_f32_16x16x32_bf16 v[26:29], v[180:183], v[188:191], v[26:29]
	v_mfma_f32_16x16x32_bf16 v[22:25], v[168:171], v[192:195], v[22:25]
	v_mfma_f32_16x16x32_bf16 v[22:25], v[172:175], v[196:199], v[22:25]
	v_mfma_f32_16x16x32_bf16 v[18:21], v[176:179], v[192:195], v[18:21]
	v_mfma_f32_16x16x32_bf16 v[18:21], v[180:183], v[196:199], v[18:21]
	v_mfma_f32_16x16x32_bf16 v[14:17], v[168:171], v[200:203], v[14:17]
	v_mfma_f32_16x16x32_bf16 v[14:17], v[172:175], v[204:207], v[14:17]
	v_mfma_f32_16x16x32_bf16 v[10:13], v[176:179], v[200:203], v[10:13]
	v_mfma_f32_16x16x32_bf16 v[10:13], v[180:183], v[204:207], v[10:13]
	v_mfma_f32_16x16x32_bf16 v[6:9], v[168:171], v[216:219], v[6:9]
	v_mfma_f32_16x16x32_bf16 v[6:9], v[172:175], v[220:223], v[6:9]
	v_mfma_f32_16x16x32_bf16 v[2:5], v[176:179], v[216:219], v[2:5]
	v_mfma_f32_16x16x32_bf16 v[2:5], v[180:183], v[220:223], v[2:5]
	s_setprio 0
	s_barrier
	s_movk_i32 s14, 0x100
	s_andn2_b64 vcc, exec, s[64:65]
	s_mov_b64 s[66:67], -1
	s_mov_b64 s[64:65], 0
	s_cbranch_vccz .LBB0_1460
	s_and_b64 vcc, exec, s[20:21]
	s_cbranch_vccz .LBB0_1463
	s_barrier
